# GU: leading half's align barrier moved ~90 instr into its epilogue (overlaps its first row-block VALU with trailing half's last MFMA block)
# baseline (speedup 1.0000x reference)
; #define PG8_BAR __builtin_amdgcn_s_barrier()
; template <int NP> __device__ __forceinline__ void load_rstd8(const float* ss, const Unit& u, int wr, int fr, int fq, float inv_n, float (&rs)[2][4]) {
;     f32x4 v[2][4];
; #pragma unroll
;     for (int ai = 0; ai < 2; ++ai)
; #pragma unroll
;         for (int m = 0; m < 4; ++m) { const int row = u.pm * BM + ai * HALF + wr * 64 + m * 16 + fr; v[ai][m] = *(const f32x4*)(ss + (size_t)row * NP + (NP == 16 ? 4 * fq : 0)); }
; #pragma unroll
;     for (int ai = 0; ai < 2; ++ai)
; #pragma unroll
;         for (int m = 0; m < 4; ++m) { float t = (v[ai][m][0] + v[ai][m][1]) + (v[ai][m][2] + v[ai][m][3]); if (NP == 16) t = quad_sum(t); rs[ai][m] = __builtin_amdgcn_rsqf(t * inv_n + kEps); }
; }
; template <class Epi, class Sched, bool ALIGN_EPI = false, bool SP2 = false>
; __device__ __forceinline__ void gemm_phase(PG8_LAS unsigned char* lds, const Gemm g, const Sched& S, const Epi& E) {
;     ...
;         if constexpr (ALIGN_EPI) { if (wr == 0) PG8_BAR; }
;         if constexpr (!Epi::AFTER_DRAIN) { E(acc, cur, wr, wc, fr, fq); S.done(cur); }
.LBB0_192:
.LBB0_194:
	s_lshl_b32 s34, s73, 8
	v_add_u32_e32 v162, s34, v147
	v_lshlrev_b32_e32 v170, 2, v238
	v_add_u32_e32 v170, 0x20000, v170
	ds_read_b32 v171, v170
	ds_read_b32 v164, v170 offset:2048
	ds_read_b32 v166, v170 offset:4096
	ds_read_b32 v160, v170 offset:6144
	ds_read_b32 v156, v170 offset:8192
	ds_read_b32 v154, v170 offset:10240
	ds_read_b32 v150, v170 offset:12288
	ds_read_b32 v158, v170 offset:14336
	ds_read_b32 v146, v170 offset:16384
	v_add_u32_e32 v152, 0x80, v162
	v_add_u32_e32 v148, 0x90, v162
	v_add_u32_e32 v144, 0xa0, v162
	v_add_u32_e32 v142, 0xb0, v162
	s_waitcnt lgkmcnt(0)
	v_cmp_eq_u32_e32 vcc, s73, v171
	s_nop 4
	s_cbranch_vccnz .Lgu_rs_hit
	v_ashrrev_i32_e32 v163, 31, v162
	v_or_b32_e32 v144, 16, v162
	v_lshlrev_b64 v[142:143], 6, v[162:163]
	v_ashrrev_i32_e32 v145, 31, v144
	v_lshl_add_u64 v[142:143], v[136:137], 0, v[142:143]
	v_lshlrev_b64 v[144:145], 6, v[144:145]
	v_lshl_add_u64 v[144:145], v[136:137], 0, v[144:145]
	global_load_dwordx4 v[164:167], v[142:143], off
	global_load_dwordx4 v[168:171], v[144:145], off
	v_or_b32_e32 v142, 32, v162
	v_ashrrev_i32_e32 v143, 31, v142
	v_or_b32_e32 v144, 48, v162
	v_lshlrev_b64 v[142:143], 6, v[142:143]
	v_ashrrev_i32_e32 v145, 31, v144
	v_add_u32_e32 v152, 0x80, v162
	v_lshl_add_u64 v[142:143], v[136:137], 0, v[142:143]
	v_lshlrev_b64 v[144:145], 6, v[144:145]
	v_ashrrev_i32_e32 v153, 31, v152
	v_lshl_add_u64 v[144:145], v[136:137], 0, v[144:145]
	global_load_dwordx4 v[172:175], v[142:143], off
	global_load_dwordx4 v[176:179], v[144:145], off
	v_lshlrev_b64 v[142:143], 6, v[152:153]
	v_lshl_add_u64 v[142:143], v[136:137], 0, v[142:143]
	global_load_dwordx4 v[180:183], v[142:143], off
	v_add_u32_e32 v148, 0x90, v162
	v_ashrrev_i32_e32 v149, 31, v148
	v_lshlrev_b64 v[142:143], 6, v[148:149]
	v_lshl_add_u64 v[142:143], v[136:137], 0, v[142:143]
	global_load_dwordx4 v[184:187], v[142:143], off
	v_add_u32_e32 v144, 0xa0, v162
	v_add_u32_e32 v142, 0xb0, v162
	v_ashrrev_i32_e32 v145, 31, v144
	v_ashrrev_i32_e32 v143, 31, v142
	v_lshlrev_b64 v[188:189], 6, v[144:145]
	v_lshlrev_b64 v[190:191], 6, v[142:143]
	v_lshl_add_u64 v[188:189], v[136:137], 0, v[188:189]
	v_lshl_add_u64 v[192:193], v[136:137], 0, v[190:191]
	global_load_dwordx4 v[188:191], v[188:189], off
	s_nop 0
	global_load_dwordx4 v[192:195], v[192:193], off
	s_waitcnt vmcnt(0)
	v_add_f32_e32 v143, v164, v165
	v_add_f32_e32 v145, v166, v167
	v_add_f32_e32 v143, v143, v145
	v_add_f32_e32 v145, v168, v169
	v_add_f32_e32 v146, v170, v171
	v_mov_b32_e32 v160, v143
	v_add_f32_e32 v145, v145, v146
	s_nop 0
	v_permlane16_swap_b32_e32 v143, v160
	v_add_f32_e32 v143, v143, v160
	v_add_f32_e32 v149, v172, v173
	v_add_f32_e32 v150, v174, v175
	v_add_f32_e32 v153, v176, v177
	v_add_f32_e32 v154, v178, v179
	v_add_f32_e32 v146, v149, v150
	v_add_f32_e32 v149, v153, v154
	v_mov_b32_e32 v153, v145
	v_add_f32_e32 v156, v180, v181
	v_add_f32_e32 v158, v182, v183
	v_permlane16_swap_b32_e32 v145, v153
	v_add_f32_e32 v150, v156, v158
	v_mov_b32_e32 v158, v143
	v_add_f32_e32 v145, v145, v153
	v_mov_b32_e32 v154, v146
	v_permlane32_swap_b32_e32 v143, v158
	v_mov_b32_e32 v153, v145
	v_permlane16_swap_b32_e32 v146, v154
	v_add_f32_e32 v143, v143, v158
	v_permlane32_swap_b32_e32 v145, v153
	v_add_f32_e32 v146, v146, v154
	v_fmamk_f32 v143, v143, 0x3a800000, v240
	v_add_f32_e32 v145, v145, v153
	v_mov_b32_e32 v154, v146
	v_rsq_f32_e32 v164, v143
	v_fmamk_f32 v143, v145, 0x3a800000, v240
	v_permlane32_swap_b32_e32 v146, v154
	v_rsq_f32_e32 v166, v143
	v_mov_b32_e32 v143, v150
	v_add_f32_e32 v146, v146, v154
	s_nop 0
	v_permlane16_swap_b32_e32 v150, v143
	v_mov_b32_e32 v156, v149
	v_fmamk_f32 v145, v146, 0x3a800000, v240
	v_add_f32_e32 v143, v150, v143
	v_permlane16_swap_b32_e32 v149, v156
	v_rsq_f32_e32 v160, v145
	v_mov_b32_e32 v145, v143
	v_add_f32_e32 v149, v149, v156
	s_nop 0
	v_permlane32_swap_b32_e32 v143, v145
	v_mov_b32_e32 v156, v149
	v_add_f32_e32 v143, v143, v145
	s_nop 0
	v_permlane32_swap_b32_e32 v149, v156
	v_fmamk_f32 v143, v143, 0x3a800000, v240
	v_add_f32_e32 v149, v149, v156
	v_rsq_f32_e32 v156, v143
	v_add_f32_e32 v143, v184, v185
	v_add_f32_e32 v145, v186, v187
	v_add_f32_e32 v143, v143, v145
	v_mov_b32_e32 v145, v143
	s_nop 1
	v_permlane16_swap_b32_e32 v143, v145
	v_add_f32_e32 v143, v143, v145
	v_mov_b32_e32 v145, v143
	s_nop 1
	v_permlane32_swap_b32_e32 v143, v145
	v_add_f32_e32 v143, v143, v145
	v_fmamk_f32 v143, v143, 0x3a800000, v240
	v_rsq_f32_e32 v154, v143
	v_add_f32_e32 v143, v188, v189
	v_add_f32_e32 v145, v190, v191
	v_add_f32_e32 v143, v143, v145
	v_mov_b32_e32 v145, v143
	s_nop 1
	v_permlane16_swap_b32_e32 v143, v145
	v_add_f32_e32 v143, v143, v145
	v_mov_b32_e32 v145, v143
	s_nop 1
	v_permlane32_swap_b32_e32 v143, v145
	v_add_f32_e32 v143, v143, v145
	v_fmamk_f32 v143, v143, 0x3a800000, v240
	v_rsq_f32_e32 v150, v143
	v_add_f32_e32 v143, v192, v193
	v_add_f32_e32 v145, v194, v195
	v_add_f32_e32 v143, v143, v145
	v_mov_b32_e32 v145, v143
	s_nop 1
	v_permlane16_swap_b32_e32 v143, v145
	v_add_f32_e32 v143, v143, v145
	v_mov_b32_e32 v145, v143
	s_nop 1
	v_permlane32_swap_b32_e32 v143, v145
	v_add_f32_e32 v143, v143, v145
	v_fmamk_f32 v146, v149, 0x3a800000, v240
	v_fmamk_f32 v143, v143, 0x3a800000, v240
	v_rsq_f32_e32 v158, v146
	v_rsq_f32_e32 v146, v143
	v_lshlrev_b32_e32 v170, 2, v238
	v_add_u32_e32 v170, 0x20000, v170
	v_mov_b32_e32 v171, s73
	ds_write_b32 v170, v171
	ds_write_b32 v170, v164 offset:2048
	ds_write_b32 v170, v166 offset:4096
	ds_write_b32 v170, v160 offset:6144
	ds_write_b32 v170, v156 offset:8192
	ds_write_b32 v170, v154 offset:10240
	ds_write_b32 v170, v150 offset:12288
	ds_write_b32 v170, v158 offset:14336
	ds_write_b32 v170, v146 offset:16384
; __device__ __forceinline__ u32x2 pack4(const f32x4 v) { u32x2 w; w.x = cvt_pk_bf16(v[0], v[1]); w.y = cvt_pk_bf16(v[2], v[3]); return w; }
; #define PG8_BAR __builtin_amdgcn_s_barrier()
;     __device__ __forceinline__ void operator()(const f32x4 (&acc)[2][2][4][2], const Unit& u, int wr, int wc, int fr, int fq) const {
;     ...
;                 const int row = u.pm * BM + ai * HALF + wr * 64 + m * 16 + fr;
;                 const float rs = rsv[ai][m];
;                 u32x2 w[2];
; #pragma unroll
;                 for (int n = 0; n < 2; ++n) {
;                     const f32x4 g = acc[ai][0][m][n] * rs, up = acc[ai][1][m][n] * rs; f32x4 o;
; #pragma unroll
;                     for (int j = 0; j < 4; ++j) { const float e = __builtin_amdgcn_exp2f(-g[j] * kLog2e); o[j] = g[j] * up[j] * __builtin_amdgcn_rcpf(1.0f + e); }
;                     w[n] = pack4(o);
;                 }
;                 *(u32x4_*)(H + (size_t)row * 2816 + u.pn * 128 + wc * 32 + fq * 8) = (u32x4_){w[0].x, w[0].y, w[1].x, w[1].y};
; template <class Epi, class Sched, bool ALIGN_EPI = false, bool SP2 = false>
; __device__ __forceinline__ void gemm_phase(PG8_LAS unsigned char* lds, const Gemm g, const Sched& S, const Epi& E) {
;     ...
;         if constexpr (ALIGN_EPI) { if (wr == 0) PG8_BAR; }
.Lgu_rs_hit:
	s_and_b64 vcc, exec, s[38:39]
	v_mov_b32_e32 v168, v120
	v_mov_b32_e32 v169, v124
	v_pk_mul_f32 v[168:169], v[168:169], v[164:165] op_sel_hi:[1,0]
	v_mul_f32_e32 v120, 0xbfb8aa3b, v168
	v_mov_b32_e32 v124, v121
	v_exp_f32_e32 v143, v120
	v_pk_mul_f32 v[120:121], v[124:125], v[164:165] op_sel_hi:[1,0]
	v_mul_f32_e32 v145, v168, v169
	v_mul_f32_e32 v124, 0xbfb8aa3b, v120
	v_exp_f32_e32 v124, v124
	v_add_f32_e32 v125, 1.0, v143
	v_rcp_f32_e32 v143, v125
	v_mov_b32_e32 v125, v126
	v_add_f32_e32 v124, 1.0, v124
	v_rcp_f32_e32 v149, v124
	v_mov_b32_e32 v124, v122
	v_pk_mul_f32 v[124:125], v[124:125], v[164:165] op_sel_hi:[1,0]
	v_mul_f32_e32 v120, v120, v121
	v_mul_f32_e32 v122, 0xbfb8aa3b, v124
	v_exp_f32_e32 v122, v122
	v_mul_f32_e32 v143, v145, v143
	v_mul_f32_e32 v145, v120, v149
	v_mov_b32_e32 v126, v123
	v_add_f32_e32 v120, 1.0, v122
	v_rcp_f32_e32 v122, v120
	v_pk_mul_f32 v[120:121], v[126:127], v[164:165] op_sel_hi:[1,0]
	v_mul_f32_e32 v124, v124, v125
	v_mul_f32_e32 v123, 0xbfb8aa3b, v120
	v_exp_f32_e32 v123, v123
	v_mul_f32_e32 v125, v120, v121
	v_mov_b32_e32 v121, v112
	v_mul_f32_e32 v124, v124, v122
	v_add_f32_e32 v120, 1.0, v123
	v_rcp_f32_e32 v126, v120
	v_mov_b32_e32 v120, v116
	v_pk_mul_f32 v[122:123], v[120:121], v[164:165] op_sel_hi:[1,0]
	v_cvt_pk_bf16_f32 v120, v143, v145
	v_mul_f32_e32 v116, v125, v126
	v_mul_f32_e32 v112, 0xbfb8aa3b, v122
	v_exp_f32_e32 v112, v112
	v_cvt_pk_bf16_f32 v121, v124, v116
	v_mul_f32_e32 v122, v122, v123
	v_add_f32_e32 v112, 1.0, v112
	v_rcp_f32_e32 v116, v112
	v_mov_b32_e32 v112, v117
	v_pk_mul_f32 v[112:113], v[112:113], v[164:165] op_sel_hi:[1,0]
	v_mul_f32_e32 v116, v122, v116
	v_mul_f32_e32 v117, 0xbfb8aa3b, v112
	v_exp_f32_e32 v117, v117
	v_mul_f32_e32 v122, v112, v113
	v_mov_b32_e32 v113, v114
	v_add_f32_e32 v112, 1.0, v117
	v_rcp_f32_e32 v117, v112
	v_mov_b32_e32 v112, v118
	v_pk_mul_f32 v[112:113], v[112:113], v[164:165] op_sel_hi:[1,0]
	v_mul_f32_e32 v117, v122, v117
	v_mul_f32_e32 v114, 0xbfb8aa3b, v112
	v_exp_f32_e32 v118, v114
	v_mov_b32_e32 v114, v119
	v_pk_mul_f32 v[114:115], v[114:115], v[164:165] op_sel_hi:[1,0]
	v_mul_f32_e32 v112, v112, v113
	v_mul_f32_e32 v119, 0xbfb8aa3b, v114
	v_exp_f32_e32 v119, v119
	v_add_f32_e32 v118, 1.0, v118
	v_rcp_f32_e32 v118, v118
	v_mul_f32_e32 v113, v114, v115
	v_add_f32_e32 v119, 1.0, v119
	v_rcp_f32_e32 v119, v119
	v_mul_f32_e32 v112, v112, v118
	v_cvt_pk_bf16_f32 v122, v116, v117
	v_mul_f32_e32 v113, v113, v119
	v_cvt_pk_bf16_f32 v123, v112, v113
	v_mov_b64_e32 v[112:113], s[90:91]
	v_mad_i64_i32 v[114:115], s[30:31], v162, s80, v[112:113]
	s_lshl_b32 s30, s72, 7
	s_ashr_i32 s31, s30, 31
	s_lshl_b64 s[30:31], s[30:31], 1
	v_lshl_add_u64 v[114:115], v[114:115], 0, s[30:31]
	v_lshl_add_u64 v[114:115], v[114:115], 0, s[18:19]
	v_lshl_add_u64 v[114:115], v[114:115], 0, v[208:209]
	global_store_dwordx4 v[114:115], v[120:123], off
	s_and_b64 vcc, exec, s[54:55]
	s_cbranch_vccz .Lgu_epi_nobar
	s_barrier
.Lgu_epi_nobar:
	s_and_b64 vcc, exec, s[38:39]
	v_mov_b32_e32 v114, v108
	v_mov_b32_e32 v115, v104
	v_pk_mul_f32 v[114:115], v[114:115], v[166:167] op_sel_hi:[1,0]
	s_nop 0
	v_mul_f32_e32 v104, 0xbfb8aa3b, v114
	v_exp_f32_e32 v108, v104
	v_mov_b32_e32 v104, v109
	v_pk_mul_f32 v[104:105], v[104:105], v[166:167] op_sel_hi:[1,0]
	v_mul_f32_e32 v114, v114, v115
	v_mul_f32_e32 v109, 0xbfb8aa3b, v104
	v_exp_f32_e32 v109, v109
	v_add_f32_e32 v108, 1.0, v108
	v_rcp_f32_e32 v115, v108
	v_mul_f32_e32 v104, v104, v105
	v_add_f32_e32 v108, 1.0, v109
	v_rcp_f32_e32 v116, v108
	v_mov_b32_e32 v108, v110
	v_mov_b32_e32 v109, v106
	v_pk_mul_f32 v[108:109], v[108:109], v[166:167] op_sel_hi:[1,0]
	v_mul_f32_e32 v110, v114, v115
	v_mul_f32_e32 v106, 0xbfb8aa3b, v108
	v_exp_f32_e32 v106, v106
	v_mul_f32_e32 v114, v104, v116
	v_add_f32_e32 v104, 1.0, v106
	v_mov_b32_e32 v106, v111
	v_rcp_f32_e32 v115, v104
	v_pk_mul_f32 v[104:105], v[106:107], v[166:167] op_sel_hi:[1,0]
	v_mul_f32_e32 v107, v108, v109
	v_mul_f32_e32 v106, 0xbfb8aa3b, v104
	v_exp_f32_e32 v106, v106
	v_mul_f32_e32 v109, v104, v105
	v_mov_b32_e32 v105, v96
	v_mul_f32_e32 v108, v107, v115
	v_add_f32_e32 v104, 1.0, v106
	v_rcp_f32_e32 v111, v104
	v_mov_b32_e32 v104, v100
	v_pk_mul_f32 v[106:107], v[104:105], v[166:167] op_sel_hi:[1,0]
	v_cvt_pk_bf16_f32 v104, v110, v114
	v_mul_f32_e32 v100, v109, v111
	v_mul_f32_e32 v96, 0xbfb8aa3b, v106
	v_exp_f32_e32 v96, v96
	v_cvt_pk_bf16_f32 v105, v108, v100
	v_mul_f32_e32 v106, v106, v107
	v_add_f32_e32 v96, 1.0, v96
	v_rcp_f32_e32 v100, v96
	v_mov_b32_e32 v96, v101
	v_pk_mul_f32 v[96:97], v[96:97], v[166:167] op_sel_hi:[1,0]
	v_mul_f32_e32 v100, v106, v100
	v_mul_f32_e32 v101, 0xbfb8aa3b, v96
	v_exp_f32_e32 v101, v101
	v_mul_f32_e32 v106, v96, v97
	v_mov_b32_e32 v97, v98
	v_add_f32_e32 v96, 1.0, v101
	v_rcp_f32_e32 v101, v96
	v_mov_b32_e32 v96, v102
	v_pk_mul_f32 v[96:97], v[96:97], v[166:167] op_sel_hi:[1,0]
	v_mul_f32_e32 v101, v106, v101
	v_mul_f32_e32 v98, 0xbfb8aa3b, v96
	v_exp_f32_e32 v102, v98
	v_mov_b32_e32 v98, v103
	v_pk_mul_f32 v[98:99], v[98:99], v[166:167] op_sel_hi:[1,0]
	v_mul_f32_e32 v96, v96, v97
	v_mul_f32_e32 v103, 0xbfb8aa3b, v98
	v_exp_f32_e32 v103, v103
	v_add_f32_e32 v102, 1.0, v102
	v_rcp_f32_e32 v102, v102
	v_mul_f32_e32 v97, v98, v99
	v_add_f32_e32 v103, 1.0, v103
	v_rcp_f32_e32 v103, v103
	v_mul_f32_e32 v96, v96, v102
	v_cvt_pk_bf16_f32 v106, v100, v101
	v_mul_f32_e32 v97, v97, v103
	v_cvt_pk_bf16_f32 v107, v96, v97
	v_add_u32_e32 v96, s34, v155
	v_mad_i64_i32 v[96:97], s[72:73], v96, s80, v[112:113]
	v_lshl_add_u64 v[96:97], v[96:97], 0, s[30:31]
	v_lshl_add_u64 v[96:97], v[96:97], 0, s[18:19]
	v_lshl_add_u64 v[96:97], v[96:97], 0, v[208:209]
; __device__ __forceinline__ u32x2 pack4(const f32x4 v) { u32x2 w; w.x = cvt_pk_bf16(v[0], v[1]); w.y = cvt_pk_bf16(v[2], v[3]); return w; }
;     __device__ __forceinline__ void operator()(const f32x4 (&acc)[2][2][4][2], const Unit& u, int wr, int wc, int fr, int fq) const {
;     ...
;                 const int row = u.pm * BM + ai * HALF + wr * 64 + m * 16 + fr;
;                 const float rs = rsv[ai][m];
;                 u32x2 w[2];
; #pragma unroll
;                 for (int n = 0; n < 2; ++n) {
;                     const f32x4 g = acc[ai][0][m][n] * rs, up = acc[ai][1][m][n] * rs; f32x4 o;
; #pragma unroll
;                     for (int j = 0; j < 4; ++j) { const float e = __builtin_amdgcn_exp2f(-g[j] * kLog2e); o[j] = g[j] * up[j] * __builtin_amdgcn_rcpf(1.0f + e); }
;                     w[n] = pack4(o);
;                 }
;                 *(u32x4_*)(H + (size_t)row * 2816 + u.pn * 128 + wc * 32 + fq * 8) = (u32x4_){w[0].x, w[0].y, w[1].x, w[1].y};
	global_store_dwordx4 v[96:97], v[104:107], off
	v_mov_b32_e32 v96, v92
	v_mov_b32_e32 v97, v88
	v_pk_mul_f32 v[96:97], v[96:97], v[160:161] op_sel_hi:[1,0]
	s_nop 0
	v_mul_f32_e32 v88, 0xbfb8aa3b, v96
	v_exp_f32_e32 v92, v88
	v_mov_b32_e32 v88, v93
	v_pk_mul_f32 v[88:89], v[88:89], v[160:161] op_sel_hi:[1,0]
	v_mul_f32_e32 v96, v96, v97
	v_mul_f32_e32 v93, 0xbfb8aa3b, v88
	v_exp_f32_e32 v93, v93
	v_add_f32_e32 v92, 1.0, v92
	v_rcp_f32_e32 v97, v92
	v_mul_f32_e32 v88, v88, v89
	v_add_f32_e32 v92, 1.0, v93
	v_rcp_f32_e32 v98, v92
	v_mov_b32_e32 v92, v94
	v_mov_b32_e32 v93, v90
	v_pk_mul_f32 v[92:93], v[92:93], v[160:161] op_sel_hi:[1,0]
	v_mul_f32_e32 v94, v96, v97
	v_mul_f32_e32 v90, 0xbfb8aa3b, v92
	v_exp_f32_e32 v90, v90
	v_mul_f32_e32 v96, v88, v98
	v_add_f32_e32 v88, 1.0, v90
	v_mov_b32_e32 v90, v95
	v_rcp_f32_e32 v97, v88
	v_pk_mul_f32 v[88:89], v[90:91], v[160:161] op_sel_hi:[1,0]
	v_mul_f32_e32 v91, v92, v93
	v_mul_f32_e32 v90, 0xbfb8aa3b, v88
	v_exp_f32_e32 v90, v90
	v_mul_f32_e32 v93, v88, v89
	v_mov_b32_e32 v89, v80
	v_mul_f32_e32 v92, v91, v97
	v_add_f32_e32 v88, 1.0, v90
	v_rcp_f32_e32 v95, v88
	v_mov_b32_e32 v88, v84
	v_pk_mul_f32 v[90:91], v[88:89], v[160:161] op_sel_hi:[1,0]
	v_cvt_pk_bf16_f32 v88, v94, v96
	v_mul_f32_e32 v84, v93, v95
	v_mul_f32_e32 v80, 0xbfb8aa3b, v90
	v_exp_f32_e32 v80, v80
	v_cvt_pk_bf16_f32 v89, v92, v84
	v_mul_f32_e32 v90, v90, v91
	v_add_f32_e32 v80, 1.0, v80
	v_rcp_f32_e32 v84, v80
	v_mov_b32_e32 v80, v85
	v_pk_mul_f32 v[80:81], v[80:81], v[160:161] op_sel_hi:[1,0]
	v_mul_f32_e32 v84, v90, v84
	v_mul_f32_e32 v85, 0xbfb8aa3b, v80
	v_exp_f32_e32 v85, v85
	v_mul_f32_e32 v90, v80, v81
	v_mov_b32_e32 v81, v82
	v_add_f32_e32 v80, 1.0, v85
	v_rcp_f32_e32 v85, v80
	v_mov_b32_e32 v80, v86
	v_pk_mul_f32 v[80:81], v[80:81], v[160:161] op_sel_hi:[1,0]
	v_mul_f32_e32 v85, v90, v85
	v_mul_f32_e32 v82, 0xbfb8aa3b, v80
	v_exp_f32_e32 v86, v82
	v_mov_b32_e32 v82, v87
	v_pk_mul_f32 v[82:83], v[82:83], v[160:161] op_sel_hi:[1,0]
	v_mul_f32_e32 v80, v80, v81
	v_mul_f32_e32 v87, 0xbfb8aa3b, v82
	v_exp_f32_e32 v87, v87
	v_add_f32_e32 v86, 1.0, v86
	v_rcp_f32_e32 v86, v86
	v_mul_f32_e32 v81, v82, v83
	v_add_f32_e32 v87, 1.0, v87
	v_rcp_f32_e32 v87, v87
	v_mul_f32_e32 v80, v80, v86
	v_cvt_pk_bf16_f32 v90, v84, v85
	v_mul_f32_e32 v81, v81, v87
	v_cvt_pk_bf16_f32 v91, v80, v81
	v_add_u32_e32 v80, s34, v157
	v_mad_i64_i32 v[80:81], s[72:73], v80, s80, v[112:113]
	v_lshl_add_u64 v[80:81], v[80:81], 0, s[30:31]
	v_lshl_add_u64 v[80:81], v[80:81], 0, s[18:19]
	v_lshl_add_u64 v[80:81], v[80:81], 0, v[208:209]
	global_store_dwordx4 v[80:81], v[88:91], off
	v_mov_b32_e32 v80, v76
	v_mov_b32_e32 v81, v72
	v_pk_mul_f32 v[80:81], v[80:81], v[158:159] op_sel_hi:[1,0]
	s_nop 0
	v_mul_f32_e32 v72, 0xbfb8aa3b, v80
	v_exp_f32_e32 v76, v72
	v_mov_b32_e32 v72, v77
	v_pk_mul_f32 v[72:73], v[72:73], v[158:159] op_sel_hi:[1,0]
	v_mul_f32_e32 v80, v80, v81
	v_mul_f32_e32 v77, 0xbfb8aa3b, v72
	v_exp_f32_e32 v77, v77
	v_add_f32_e32 v76, 1.0, v76
	v_rcp_f32_e32 v81, v76
	v_mul_f32_e32 v72, v72, v73
	v_add_f32_e32 v76, 1.0, v77
	v_rcp_f32_e32 v82, v76
	v_mov_b32_e32 v76, v78
	v_mov_b32_e32 v77, v74
	v_pk_mul_f32 v[76:77], v[76:77], v[158:159] op_sel_hi:[1,0]
	v_mul_f32_e32 v78, v80, v81
	v_mul_f32_e32 v74, 0xbfb8aa3b, v76
	v_exp_f32_e32 v74, v74
	v_mul_f32_e32 v80, v72, v82
	v_add_f32_e32 v72, 1.0, v74
	v_mov_b32_e32 v74, v79
	v_rcp_f32_e32 v81, v72
	v_pk_mul_f32 v[72:73], v[74:75], v[158:159] op_sel_hi:[1,0]
	v_mul_f32_e32 v75, v76, v77
	v_mul_f32_e32 v74, 0xbfb8aa3b, v72
	v_exp_f32_e32 v74, v74
	v_mul_f32_e32 v77, v72, v73
	v_mov_b32_e32 v73, v64
	v_mul_f32_e32 v76, v75, v81
	v_add_f32_e32 v72, 1.0, v74
	v_rcp_f32_e32 v79, v72
	v_mov_b32_e32 v72, v68
	v_pk_mul_f32 v[74:75], v[72:73], v[158:159] op_sel_hi:[1,0]
	v_cvt_pk_bf16_f32 v72, v78, v80
	v_mul_f32_e32 v68, v77, v79
	v_mul_f32_e32 v64, 0xbfb8aa3b, v74
	v_exp_f32_e32 v64, v64
	v_cvt_pk_bf16_f32 v73, v76, v68
	v_mul_f32_e32 v74, v74, v75
	v_add_f32_e32 v64, 1.0, v64
	v_rcp_f32_e32 v68, v64
	v_mov_b32_e32 v64, v69
	v_pk_mul_f32 v[64:65], v[64:65], v[158:159] op_sel_hi:[1,0]
	v_mul_f32_e32 v68, v74, v68
	v_mul_f32_e32 v69, 0xbfb8aa3b, v64
	v_exp_f32_e32 v69, v69
	v_mul_f32_e32 v74, v64, v65
	v_mov_b32_e32 v65, v66
	v_add_f32_e32 v64, 1.0, v69
	v_rcp_f32_e32 v69, v64
	v_mov_b32_e32 v64, v70
	v_pk_mul_f32 v[64:65], v[64:65], v[158:159] op_sel_hi:[1,0]
	v_mul_f32_e32 v69, v74, v69
	v_mul_f32_e32 v66, 0xbfb8aa3b, v64
	v_exp_f32_e32 v70, v66
	v_mov_b32_e32 v66, v71
	v_pk_mul_f32 v[66:67], v[66:67], v[158:159] op_sel_hi:[1,0]
	v_mul_f32_e32 v64, v64, v65
	v_mul_f32_e32 v71, 0xbfb8aa3b, v66
	v_exp_f32_e32 v71, v71
	v_add_f32_e32 v70, 1.0, v70
	v_rcp_f32_e32 v70, v70
	v_mul_f32_e32 v65, v66, v67
	v_add_f32_e32 v71, 1.0, v71
	v_rcp_f32_e32 v71, v71
	v_mul_f32_e32 v64, v64, v70
	v_cvt_pk_bf16_f32 v74, v68, v69
	v_mul_f32_e32 v65, v65, v71
	v_cvt_pk_bf16_f32 v75, v64, v65
	v_add_u32_e32 v64, s34, v159
	v_mad_i64_i32 v[64:65], s[34:35], v64, s80, v[112:113]
	v_lshl_add_u64 v[64:65], v[64:65], 0, s[30:31]
	v_lshl_add_u64 v[64:65], v[64:65], 0, s[18:19]
	v_lshl_add_u64 v[64:65], v[64:65], 0, v[208:209]
	global_store_dwordx4 v[64:65], v[72:75], off
	v_mov_b32_e32 v64, v60
	v_mov_b32_e32 v65, v56
	v_pk_mul_f32 v[64:65], v[64:65], v[156:157] op_sel_hi:[1,0]
	s_nop 0
	v_mul_f32_e32 v56, 0xbfb8aa3b, v64
	v_exp_f32_e32 v60, v56
	v_mov_b32_e32 v56, v61
	v_pk_mul_f32 v[56:57], v[56:57], v[156:157] op_sel_hi:[1,0]
	v_mul_f32_e32 v64, v64, v65
	v_mul_f32_e32 v61, 0xbfb8aa3b, v56
	v_exp_f32_e32 v61, v61
	v_add_f32_e32 v60, 1.0, v60
	v_rcp_f32_e32 v65, v60
	v_mul_f32_e32 v56, v56, v57
	v_add_f32_e32 v60, 1.0, v61
; __device__ __forceinline__ u32x2 pack4(const f32x4 v) { u32x2 w; w.x = cvt_pk_bf16(v[0], v[1]); w.y = cvt_pk_bf16(v[2], v[3]); return w; }
;     __device__ __forceinline__ void operator()(const f32x4 (&acc)[2][2][4][2], const Unit& u, int wr, int wc, int fr, int fq) const {
;     ...
;                 const int row = u.pm * BM + ai * HALF + wr * 64 + m * 16 + fr;
;                 const float rs = rsv[ai][m];
;                 u32x2 w[2];
; #pragma unroll
;                 for (int n = 0; n < 2; ++n) {
;                     const f32x4 g = acc[ai][0][m][n] * rs, up = acc[ai][1][m][n] * rs; f32x4 o;
; #pragma unroll
;                     for (int j = 0; j < 4; ++j) { const float e = __builtin_amdgcn_exp2f(-g[j] * kLog2e); o[j] = g[j] * up[j] * __builtin_amdgcn_rcpf(1.0f + e); }
;                     w[n] = pack4(o);
;                 }
;                 *(u32x4_*)(H + (size_t)row * 2816 + u.pn * 128 + wc * 32 + fq * 8) = (u32x4_){w[0].x, w[0].y, w[1].x, w[1].y};
	v_rcp_f32_e32 v66, v60
	v_mov_b32_e32 v60, v62
	v_mov_b32_e32 v61, v58
	v_pk_mul_f32 v[60:61], v[60:61], v[156:157] op_sel_hi:[1,0]
	v_mul_f32_e32 v62, v64, v65
	v_mul_f32_e32 v58, 0xbfb8aa3b, v60
	v_exp_f32_e32 v58, v58
	v_mul_f32_e32 v64, v56, v66
	v_add_f32_e32 v56, 1.0, v58
	v_mov_b32_e32 v58, v63
	v_rcp_f32_e32 v65, v56
	v_pk_mul_f32 v[56:57], v[58:59], v[156:157] op_sel_hi:[1,0]
	v_mul_f32_e32 v59, v60, v61
	v_mul_f32_e32 v58, 0xbfb8aa3b, v56
	v_exp_f32_e32 v58, v58
	v_mul_f32_e32 v61, v56, v57
	v_mov_b32_e32 v57, v48
	v_mul_f32_e32 v60, v59, v65
	v_add_f32_e32 v56, 1.0, v58
	v_rcp_f32_e32 v63, v56
	v_mov_b32_e32 v56, v52
	v_pk_mul_f32 v[58:59], v[56:57], v[156:157] op_sel_hi:[1,0]
	v_cvt_pk_bf16_f32 v56, v62, v64
	v_mul_f32_e32 v52, v61, v63
	v_mul_f32_e32 v48, 0xbfb8aa3b, v58
	v_exp_f32_e32 v48, v48
	v_cvt_pk_bf16_f32 v57, v60, v52
	v_mul_f32_e32 v58, v58, v59
	v_add_f32_e32 v48, 1.0, v48
	v_rcp_f32_e32 v52, v48
	v_mov_b32_e32 v48, v53
	v_pk_mul_f32 v[48:49], v[48:49], v[156:157] op_sel_hi:[1,0]
	v_mul_f32_e32 v52, v58, v52
	v_mul_f32_e32 v53, 0xbfb8aa3b, v48
	v_exp_f32_e32 v53, v53
	v_mul_f32_e32 v58, v48, v49
	v_mov_b32_e32 v49, v50
	v_add_f32_e32 v48, 1.0, v53
	v_rcp_f32_e32 v53, v48
	v_mov_b32_e32 v48, v54
	v_pk_mul_f32 v[48:49], v[48:49], v[156:157] op_sel_hi:[1,0]
	v_mul_f32_e32 v53, v58, v53
	v_mul_f32_e32 v50, 0xbfb8aa3b, v48
	v_exp_f32_e32 v54, v50
	v_mov_b32_e32 v50, v55
	v_pk_mul_f32 v[50:51], v[50:51], v[156:157] op_sel_hi:[1,0]
	v_mul_f32_e32 v48, v48, v49
	v_mul_f32_e32 v55, 0xbfb8aa3b, v50
	v_exp_f32_e32 v55, v55
	v_add_f32_e32 v54, 1.0, v54
	v_rcp_f32_e32 v54, v54
	v_mul_f32_e32 v49, v50, v51
	v_add_f32_e32 v55, 1.0, v55
	v_rcp_f32_e32 v55, v55
	v_mul_f32_e32 v48, v48, v54
	v_cvt_pk_bf16_f32 v58, v52, v53
	v_mul_f32_e32 v49, v49, v55
	v_cvt_pk_bf16_f32 v59, v48, v49
	v_mad_i64_i32 v[48:49], s[34:35], v152, s80, v[112:113]
	v_lshl_add_u64 v[48:49], v[48:49], 0, s[30:31]
	v_lshl_add_u64 v[48:49], v[48:49], 0, s[18:19]
	v_lshl_add_u64 v[48:49], v[48:49], 0, v[208:209]
	global_store_dwordx4 v[48:49], v[56:59], off
	v_mov_b32_e32 v48, v44
	v_mov_b32_e32 v49, v40
	v_pk_mul_f32 v[48:49], v[48:49], v[154:155] op_sel_hi:[1,0]
	s_nop 0
	v_mul_f32_e32 v40, 0xbfb8aa3b, v48
	v_exp_f32_e32 v44, v40
	v_mov_b32_e32 v40, v45
	v_pk_mul_f32 v[40:41], v[40:41], v[154:155] op_sel_hi:[1,0]
	v_mul_f32_e32 v48, v48, v49
	v_mul_f32_e32 v45, 0xbfb8aa3b, v40
	v_exp_f32_e32 v45, v45
	v_add_f32_e32 v44, 1.0, v44
	v_rcp_f32_e32 v49, v44
	v_mul_f32_e32 v40, v40, v41
	v_add_f32_e32 v44, 1.0, v45
	v_rcp_f32_e32 v50, v44
	v_mov_b32_e32 v44, v46
	v_mov_b32_e32 v45, v42
	v_pk_mul_f32 v[44:45], v[44:45], v[154:155] op_sel_hi:[1,0]
	v_mul_f32_e32 v46, v48, v49
	v_mul_f32_e32 v42, 0xbfb8aa3b, v44
	v_exp_f32_e32 v42, v42
	v_mul_f32_e32 v48, v40, v50
	v_add_f32_e32 v40, 1.0, v42
	v_mov_b32_e32 v42, v47
	v_rcp_f32_e32 v49, v40
	v_pk_mul_f32 v[40:41], v[42:43], v[154:155] op_sel_hi:[1,0]
	v_mul_f32_e32 v43, v44, v45
	v_mul_f32_e32 v42, 0xbfb8aa3b, v40
	v_exp_f32_e32 v42, v42
	v_mul_f32_e32 v45, v40, v41
	v_mov_b32_e32 v41, v32
	v_mul_f32_e32 v44, v43, v49
	v_add_f32_e32 v40, 1.0, v42
	v_rcp_f32_e32 v47, v40
	v_mov_b32_e32 v40, v36
	v_pk_mul_f32 v[42:43], v[40:41], v[154:155] op_sel_hi:[1,0]
	v_cvt_pk_bf16_f32 v40, v46, v48
	v_mul_f32_e32 v36, v45, v47
	v_mul_f32_e32 v32, 0xbfb8aa3b, v42
	v_exp_f32_e32 v32, v32
	v_cvt_pk_bf16_f32 v41, v44, v36
	v_mul_f32_e32 v42, v42, v43
	v_add_f32_e32 v32, 1.0, v32
	v_rcp_f32_e32 v36, v32
	v_mov_b32_e32 v32, v37
	v_pk_mul_f32 v[32:33], v[32:33], v[154:155] op_sel_hi:[1,0]
	v_mul_f32_e32 v36, v42, v36
	v_mul_f32_e32 v37, 0xbfb8aa3b, v32
	v_exp_f32_e32 v37, v37
	v_mul_f32_e32 v42, v32, v33
	v_mov_b32_e32 v33, v34
	v_add_f32_e32 v32, 1.0, v37
	v_rcp_f32_e32 v37, v32
	v_mov_b32_e32 v32, v38
	v_pk_mul_f32 v[32:33], v[32:33], v[154:155] op_sel_hi:[1,0]
	v_mul_f32_e32 v37, v42, v37
	v_mul_f32_e32 v34, 0xbfb8aa3b, v32
	v_exp_f32_e32 v38, v34
	v_mov_b32_e32 v34, v39
	v_pk_mul_f32 v[34:35], v[34:35], v[154:155] op_sel_hi:[1,0]
	v_mul_f32_e32 v32, v32, v33
	v_mul_f32_e32 v39, 0xbfb8aa3b, v34
	v_exp_f32_e32 v39, v39
	v_add_f32_e32 v38, 1.0, v38
	v_rcp_f32_e32 v38, v38
	v_mul_f32_e32 v33, v34, v35
	v_add_f32_e32 v39, 1.0, v39
	v_rcp_f32_e32 v39, v39
	v_mul_f32_e32 v32, v32, v38
	v_cvt_pk_bf16_f32 v42, v36, v37
	v_mul_f32_e32 v33, v33, v39
	v_cvt_pk_bf16_f32 v43, v32, v33
	v_mad_i64_i32 v[32:33], s[34:35], v148, s80, v[112:113]
	v_lshl_add_u64 v[32:33], v[32:33], 0, s[30:31]
	v_lshl_add_u64 v[32:33], v[32:33], 0, s[18:19]
	v_lshl_add_u64 v[32:33], v[32:33], 0, v[208:209]
	global_store_dwordx4 v[32:33], v[40:43], off
	v_mov_b32_e32 v32, v28
	v_mov_b32_e32 v33, v24
	v_pk_mul_f32 v[32:33], v[32:33], v[150:151] op_sel_hi:[1,0]
	s_nop 0
	v_mul_f32_e32 v24, 0xbfb8aa3b, v32
	v_exp_f32_e32 v28, v24
	v_mov_b32_e32 v24, v29
	v_pk_mul_f32 v[24:25], v[24:25], v[150:151] op_sel_hi:[1,0]
; __device__ __forceinline__ u32x2 pack4(const f32x4 v) { u32x2 w; w.x = cvt_pk_bf16(v[0], v[1]); w.y = cvt_pk_bf16(v[2], v[3]); return w; }
; #define PG8_BAR __builtin_amdgcn_s_barrier()
;     __device__ __forceinline__ void operator()(const f32x4 (&acc)[2][2][4][2], const Unit& u, int wr, int wc, int fr, int fq) const {
;     ...
;                 const int row = u.pm * BM + ai * HALF + wr * 64 + m * 16 + fr;
;                 const float rs = rsv[ai][m];
;                 u32x2 w[2];
; #pragma unroll
;                 for (int n = 0; n < 2; ++n) {
;                     const f32x4 g = acc[ai][0][m][n] * rs, up = acc[ai][1][m][n] * rs; f32x4 o;
; #pragma unroll
;                     for (int j = 0; j < 4; ++j) { const float e = __builtin_amdgcn_exp2f(-g[j] * kLog2e); o[j] = g[j] * up[j] * __builtin_amdgcn_rcpf(1.0f + e); }
;                     w[n] = pack4(o);
;                 }
;                 *(u32x4_*)(H + (size_t)row * 2816 + u.pn * 128 + wc * 32 + fq * 8) = (u32x4_){w[0].x, w[0].y, w[1].x, w[1].y};
; template <class Epi, class Sched, bool ALIGN_EPI = false, bool SP2 = false>
; __device__ __forceinline__ void gemm_phase(PG8_LAS unsigned char* lds, const Gemm g, const Sched& S, const Epi& E) {
;     ...
;         if (!has_next) break;
; #pragma unroll
;         for (int a = 0; a < 2; ++a)
; #pragma unroll
;             for (int b = 0; b < 2; ++b)
; #pragma unroll
;                 for (int m = 0; m < 4; ++m)
; #pragma unroll
;                     for (int n = 0; n < 2; ++n) acc[a][b][m][n] = (f32x4){0.f, 0.f, 0.f, 0.f};
;         cur = nxt; cA = nA; cB = nB; ++ui;
;         if constexpr (ALIGN_EPI) { if (wr == 1) PG8_BAR; }
	v_mul_f32_e32 v32, v32, v33
	v_mul_f32_e32 v29, 0xbfb8aa3b, v24
	v_exp_f32_e32 v29, v29
	v_add_f32_e32 v28, 1.0, v28
	v_rcp_f32_e32 v33, v28
	v_mul_f32_e32 v24, v24, v25
	v_add_f32_e32 v28, 1.0, v29
	v_rcp_f32_e32 v34, v28
	v_mov_b32_e32 v28, v30
	v_mov_b32_e32 v29, v26
	v_pk_mul_f32 v[28:29], v[28:29], v[150:151] op_sel_hi:[1,0]
	v_mul_f32_e32 v30, v32, v33
	v_mul_f32_e32 v26, 0xbfb8aa3b, v28
	v_exp_f32_e32 v26, v26
	v_mul_f32_e32 v32, v24, v34
	v_add_f32_e32 v24, 1.0, v26
	v_mov_b32_e32 v26, v31
	v_rcp_f32_e32 v33, v24
	v_pk_mul_f32 v[24:25], v[26:27], v[150:151] op_sel_hi:[1,0]
	v_mul_f32_e32 v27, v28, v29
	v_mul_f32_e32 v26, 0xbfb8aa3b, v24
	v_exp_f32_e32 v26, v26
	v_mul_f32_e32 v29, v24, v25
	v_mov_b32_e32 v25, v16
	v_mul_f32_e32 v28, v27, v33
	v_add_f32_e32 v24, 1.0, v26
	v_rcp_f32_e32 v31, v24
	v_mov_b32_e32 v24, v20
	v_pk_mul_f32 v[26:27], v[24:25], v[150:151] op_sel_hi:[1,0]
	v_cvt_pk_bf16_f32 v24, v30, v32
	v_mul_f32_e32 v20, v29, v31
	v_mul_f32_e32 v16, 0xbfb8aa3b, v26
	v_exp_f32_e32 v16, v16
	v_cvt_pk_bf16_f32 v25, v28, v20
	v_mul_f32_e32 v26, v26, v27
	v_add_f32_e32 v16, 1.0, v16
	v_rcp_f32_e32 v20, v16
	v_mov_b32_e32 v16, v21
	v_pk_mul_f32 v[16:17], v[16:17], v[150:151] op_sel_hi:[1,0]
	v_mul_f32_e32 v20, v26, v20
	v_mul_f32_e32 v21, 0xbfb8aa3b, v16
	v_exp_f32_e32 v21, v21
	v_mul_f32_e32 v26, v16, v17
	v_mov_b32_e32 v17, v18
	v_add_f32_e32 v16, 1.0, v21
	v_rcp_f32_e32 v21, v16
	v_mov_b32_e32 v16, v22
	v_pk_mul_f32 v[16:17], v[16:17], v[150:151] op_sel_hi:[1,0]
	v_mul_f32_e32 v21, v26, v21
	v_mul_f32_e32 v18, 0xbfb8aa3b, v16
	v_exp_f32_e32 v22, v18
	v_mov_b32_e32 v18, v23
	v_pk_mul_f32 v[18:19], v[18:19], v[150:151] op_sel_hi:[1,0]
	v_mul_f32_e32 v16, v16, v17
	v_mul_f32_e32 v23, 0xbfb8aa3b, v18
	v_exp_f32_e32 v23, v23
	v_add_f32_e32 v22, 1.0, v22
	v_rcp_f32_e32 v22, v22
	v_mul_f32_e32 v17, v18, v19
	v_add_f32_e32 v23, 1.0, v23
	v_rcp_f32_e32 v23, v23
	v_mul_f32_e32 v16, v16, v22
	v_cvt_pk_bf16_f32 v26, v20, v21
	v_mul_f32_e32 v17, v17, v23
	v_cvt_pk_bf16_f32 v27, v16, v17
	v_mad_i64_i32 v[16:17], s[34:35], v144, s80, v[112:113]
	v_lshl_add_u64 v[16:17], v[16:17], 0, s[30:31]
	v_lshl_add_u64 v[16:17], v[16:17], 0, s[18:19]
	v_lshl_add_u64 v[16:17], v[16:17], 0, v[208:209]
	global_store_dwordx4 v[16:17], v[24:27], off
	v_mov_b32_e32 v16, v12
	v_mov_b32_e32 v17, v8
	v_pk_mul_f32 v[16:17], v[16:17], v[146:147] op_sel_hi:[1,0]
	s_nop 0
	v_mul_f32_e32 v8, 0xbfb8aa3b, v16
	v_exp_f32_e32 v12, v8
	v_mov_b32_e32 v8, v13
	v_pk_mul_f32 v[8:9], v[8:9], v[146:147] op_sel_hi:[1,0]
	v_mul_f32_e32 v16, v16, v17
	v_mul_f32_e32 v13, 0xbfb8aa3b, v8
	v_exp_f32_e32 v13, v13
	v_add_f32_e32 v12, 1.0, v12
	v_rcp_f32_e32 v17, v12
	v_mul_f32_e32 v8, v8, v9
	v_add_f32_e32 v12, 1.0, v13
	v_rcp_f32_e32 v18, v12
	v_mov_b32_e32 v12, v14
	v_mov_b32_e32 v13, v10
	v_pk_mul_f32 v[12:13], v[12:13], v[146:147] op_sel_hi:[1,0]
	v_mul_f32_e32 v14, v16, v17
	v_mul_f32_e32 v10, 0xbfb8aa3b, v12
	v_exp_f32_e32 v10, v10
	v_mul_f32_e32 v16, v8, v18
	v_add_f32_e32 v8, 1.0, v10
	v_mov_b32_e32 v10, v15
	v_rcp_f32_e32 v17, v8
	v_pk_mul_f32 v[8:9], v[10:11], v[146:147] op_sel_hi:[1,0]
	v_mul_f32_e32 v11, v12, v13
	v_mul_f32_e32 v10, 0xbfb8aa3b, v8
	v_exp_f32_e32 v10, v10
	v_mul_f32_e32 v13, v8, v9
	v_mov_b32_e32 v9, v0
	v_mul_f32_e32 v12, v11, v17
	v_add_f32_e32 v8, 1.0, v10
	v_rcp_f32_e32 v15, v8
	v_mov_b32_e32 v8, v4
	v_pk_mul_f32 v[10:11], v[8:9], v[146:147] op_sel_hi:[1,0]
	v_cvt_pk_bf16_f32 v8, v14, v16
	v_mul_f32_e32 v4, v13, v15
	v_mul_f32_e32 v0, 0xbfb8aa3b, v10
	v_exp_f32_e32 v0, v0
	v_cvt_pk_bf16_f32 v9, v12, v4
	v_mul_f32_e32 v10, v10, v11
	v_add_f32_e32 v0, 1.0, v0
	v_rcp_f32_e32 v4, v0
	v_mov_b32_e32 v0, v5
	v_pk_mul_f32 v[0:1], v[0:1], v[146:147] op_sel_hi:[1,0]
	v_mul_f32_e32 v4, v10, v4
	v_mul_f32_e32 v5, 0xbfb8aa3b, v0
	v_exp_f32_e32 v5, v5
	v_mul_f32_e32 v10, v0, v1
	v_mov_b32_e32 v1, v2
	v_add_f32_e32 v0, 1.0, v5
	v_rcp_f32_e32 v5, v0
	v_mov_b32_e32 v0, v6
	v_pk_mul_f32 v[0:1], v[0:1], v[146:147] op_sel_hi:[1,0]
	v_mul_f32_e32 v5, v10, v5
	v_mul_f32_e32 v2, 0xbfb8aa3b, v0
	v_exp_f32_e32 v6, v2
	v_mov_b32_e32 v2, v7
	v_pk_mul_f32 v[2:3], v[2:3], v[146:147] op_sel_hi:[1,0]
	v_mul_f32_e32 v0, v0, v1
	v_mul_f32_e32 v7, 0xbfb8aa3b, v2
	v_exp_f32_e32 v7, v7
	v_add_f32_e32 v6, 1.0, v6
	v_rcp_f32_e32 v6, v6
	v_mul_f32_e32 v1, v2, v3
	v_add_f32_e32 v7, 1.0, v7
	v_rcp_f32_e32 v7, v7
	v_mul_f32_e32 v0, v0, v6
	v_cvt_pk_bf16_f32 v10, v4, v5
	v_mul_f32_e32 v1, v1, v7
	v_cvt_pk_bf16_f32 v11, v0, v1
	v_mad_i64_i32 v[0:1], s[34:35], v142, s80, v[112:113]
	v_lshl_add_u64 v[0:1], v[0:1], 0, s[30:31]
	v_lshl_add_u64 v[0:1], v[0:1], 0, s[18:19]
	v_lshl_add_u64 v[0:1], v[0:1], 0, v[208:209]
	s_mov_b64 s[30:31], -1
	global_store_dwordx4 v[0:1], v[8:11], off
	s_cbranch_vccnz .LBB0_182
	s_andn2_b64 vcc, exec, s[28:29]
	s_cbranch_vccnz .LBB0_181
	s_barrier
	s_branch .LBB0_181
